# FFN-up meta-row tail unit: 4 serialized column-constant loads hoisted to unit start behind existing waits; on v35
# speedup vs baseline: 1.0058x; 1.0023x over previous
.LBB0_954:
	s_and_b32 s17, s3, 0xffffff00
	s_and_b32 s16, s1, 0x60
	v_or_b32_e32 v2, s17, v1
	v_or_b32_e32 v2, s16, v2
	v_ashrrev_i32_e32 v3, 31, v2
	v_lshlrev_b64 v[2:3], 11, v[2:3]
	v_lshl_add_u64 v[86:87], v[36:37], 0, v[2:3]
	global_load_dwordx4 v[18:21], v[34:35], off
	global_load_dwordx4 v[2:5], v[86:87], off
	v_add_co_u32_e32 v90, vcc, 0x40000, v86
	s_ashr_i32 s17, s0, 2
	s_nop 0
	v_addc_co_u32_e32 v91, vcc, 0, v87, vcc
	global_load_dwordx4 v[22:25], v[90:91], off
	global_load_dwordx4 v[46:49], v[34:35], off offset:32
	global_load_dwordx4 v[50:53], v[86:87], off offset:32
	global_load_dwordx4 v[54:57], v[90:91], off offset:32
	global_load_dwordx4 v[58:61], v[34:35], off offset:64
	global_load_dwordx4 v[62:65], v[86:87], off offset:64
	global_load_dwordx4 v[66:69], v[90:91], off offset:64
	global_load_dwordx4 v[70:73], v[34:35], off offset:96
	global_load_dwordx4 v[74:77], v[86:87], off offset:96
	global_load_dwordx4 v[78:81], v[90:91], off offset:96
	s_lshl_b32 s18, s17, 8
	s_or_b32 s18, s18, s16
	s_lshl_b32 s17, s17, 7
	s_or_b32 s16, s17, s16
	s_addk_i32 s1, 0x2000
	s_addk_i32 s3, 0x4000
	s_waitcnt vmcnt(0) lgkmcnt(0)
	v_mfma_f32_32x32x16_bf16 v[2:17], v[18:21], v[2:5], 0
	v_mfma_f32_32x32x16_bf16 v[18:33], v[18:21], v[22:25], 0
	v_mfma_f32_32x32x16_bf16 v[2:17], v[46:49], v[50:53], v[2:17]
	v_mfma_f32_32x32x16_bf16 v[18:33], v[46:49], v[54:57], v[18:33]
	v_mfma_f32_32x32x16_bf16 v[2:17], v[58:61], v[62:65], v[2:17]
	v_mfma_f32_32x32x16_bf16 v[18:33], v[58:61], v[66:69], v[18:33]
	v_mfma_f32_32x32x16_bf16 v[2:17], v[70:73], v[74:77], v[2:17]
	v_mfma_f32_32x32x16_bf16 v[18:33], v[70:73], v[78:81], v[18:33]
	global_load_dwordx4 v[46:49], v[34:35], off offset:128
	global_load_dwordx4 v[50:53], v[86:87], off offset:128
	global_load_dwordx4 v[54:57], v[90:91], off offset:128
	global_load_dwordx4 v[58:61], v[34:35], off offset:160
	global_load_dwordx4 v[62:65], v[86:87], off offset:160
	global_load_dwordx4 v[66:69], v[90:91], off offset:160
	global_load_dwordx4 v[70:73], v[34:35], off offset:192
	global_load_dwordx4 v[74:77], v[86:87], off offset:192
	global_load_dwordx4 v[78:81], v[90:91], off offset:192
	global_load_dwordx4 v[82:85], v[34:35], off offset:224
	s_nop 0
	global_load_dwordx4 v[86:89], v[86:87], off offset:224
	s_nop 0
	global_load_dwordx4 v[90:93], v[90:91], off offset:224
	s_waitcnt vmcnt(0) lgkmcnt(0)
	v_mfma_f32_32x32x16_bf16 v[2:17], v[46:49], v[50:53], v[2:17]
	v_mfma_f32_32x32x16_bf16 v[18:33], v[46:49], v[54:57], v[18:33]
	v_or_b32_e32 v46, s18, v43
	v_ashrrev_i32_e32 v47, 31, v46
	v_lshlrev_b64 v[94:95], 3, v[46:47]
	v_lshl_add_u64 v[96:97], s[10:11], 0, v[94:95]
	v_lshl_add_u64 v[94:95], s[12:13], 0, v[94:95]
	global_load_dwordx4 v[98:101], v[96:97], off
	global_load_dwordx4 v[102:105], v[94:95], off
	global_load_dwordx4 v[106:109], v[96:97], off offset:1024
	global_load_dwordx4 v[110:113], v[94:95], off offset:1024
	v_mfma_f32_32x32x16_bf16 v[2:17], v[58:61], v[62:65], v[2:17]
	v_mfma_f32_32x32x16_bf16 v[18:33], v[58:61], v[66:69], v[18:33]
	v_mfma_f32_32x32x16_bf16 v[2:17], v[70:73], v[74:77], v[2:17]
	v_mfma_f32_32x32x16_bf16 v[18:33], v[70:73], v[78:81], v[18:33]
	v_mfma_f32_32x32x16_bf16 v[2:17], v[82:85], v[86:89], v[2:17]
	v_mfma_f32_32x32x16_bf16 v[18:33], v[82:85], v[90:93], v[18:33]
	s_nop 11
	ds_write2_b32 v42, v2, v18 offset1:32
	ds_write2_b32 v42, v3, v19 offset0:64 offset1:96
	ds_write2_b32 v42, v4, v20 offset0:128 offset1:160
	ds_write2_b32 v42, v5, v21 offset0:192 offset1:224
	v_add_u32_e32 v2, 0x800, v42
	ds_write2_b32 v2, v6, v22 offset1:32
	ds_write2_b32 v2, v7, v23 offset0:64 offset1:96
	ds_write2_b32 v2, v8, v24 offset0:128 offset1:160
	ds_write2_b32 v2, v9, v25 offset0:192 offset1:224
	v_add_u32_e32 v2, 0x1000, v42
	ds_write2_b32 v2, v10, v26 offset1:32
	ds_write2_b32 v2, v11, v27 offset0:64 offset1:96
	ds_write2_b32 v2, v12, v28 offset0:128 offset1:160
	ds_write2_b32 v2, v13, v29 offset0:192 offset1:224
	v_add_u32_e32 v2, 0x1800, v42
	ds_write2_b32 v2, v14, v30 offset1:32
	ds_write2_b32 v2, v15, v31 offset0:64 offset1:96
	ds_write2_b32 v2, v16, v32 offset0:128 offset1:160
	ds_write2_b32 v2, v17, v33 offset0:192 offset1:224
	s_waitcnt lgkmcnt(0)
	s_barrier
	ds_read2_b64 v[2:5], v44 offset1:16
	s_waitcnt lgkmcnt(0)
	v_pk_add_f32 v[32:33], v[4:5], 0 op_sel_hi:[1,0]
	v_add_u32_e32 v4, 0x2000, v44
	ds_read2_b64 v[12:15], v4 offset1:16
	global_load_dwordx4 v[4:7], v[38:39], off
	global_load_dwordx4 v[8:11], v[38:39], off offset:16
	global_load_dwordx4 v[16:19], v[38:39], off offset:32
	global_load_dwordx4 v[20:23], v[38:39], off offset:48
	global_load_dwordx4 v[24:27], v[38:39], off offset:64
	global_load_dwordx4 v[28:31], v[38:39], off offset:80
	v_pk_add_f32 v[2:3], v[2:3], 0 op_sel_hi:[1,0]
	s_waitcnt vmcnt(0) lgkmcnt(0)
	v_pk_add_f32 v[4:5], v[4:5], v[6:7]
	s_nop 0
	v_pk_add_f32 v[4:5], v[4:5], 0 op_sel_hi:[1,0]
	v_pk_add_f32 v[6:7], v[8:9], v[10:11]
	v_pk_add_f32 v[12:13], v[2:3], v[12:13]
	v_add_f32_e32 v49, v25, v27
	v_mov_b32_e32 v25, v28
	v_mov_b32_e32 v27, v30
	v_pk_add_f32 v[50:51], v[24:25], v[26:27]
	v_add_f32_e32 v53, v29, v31
	global_load_dwordx4 v[24:27], v[38:39], off offset:96
	global_load_dwordx4 v[28:31], v[38:39], off offset:112
	v_pk_add_f32 v[4:5], v[4:5], v[6:7]
	v_pk_add_f32 v[6:7], v[16:17], v[18:19]
	v_mov_b32_e32 v48, v50
	v_pk_add_f32 v[4:5], v[4:5], v[6:7]
	v_pk_add_f32 v[6:7], v[20:21], v[22:23]
	v_mov_b32_e32 v52, v51
	v_pk_add_f32 v[4:5], v[4:5], v[6:7]
	v_pk_add_f32 v[18:19], v[32:33], v[14:15]
	v_pk_add_f32 v[4:5], v[4:5], v[48:49]
	v_lshlrev_b64 v[8:9], 3, v[46:47]
	v_pk_add_f32 v[4:5], v[4:5], v[52:53]
	v_lshl_add_u64 v[10:11], s[10:11], 0, v[8:9]
	v_lshl_add_u64 v[8:9], s[12:13], 0, v[8:9]
	v_or_b32_e32 v2, s16, v43
	s_add_i32 s16, s0, 0x100
	s_cmpk_lt_i32 s0, 0xff58
	s_mov_b32 s0, s16
	s_waitcnt vmcnt(0) lgkmcnt(0)
	v_add_f32_e32 v55, v25, v27
	v_mov_b32_e32 v25, v28
	v_mov_b32_e32 v27, v30
	v_pk_add_f32 v[24:25], v[24:25], v[26:27]
	v_add_f32_e32 v27, v29, v31
	v_mov_b32_e32 v54, v24
	v_pk_add_f32 v[4:5], v[4:5], v[54:55]
	v_mov_b32_e32 v26, v25
	v_pk_add_f32 v[4:5], v[4:5], v[26:27]
	s_nop 0
	v_pk_mul_f32 v[6:7], v[4:5], s[64:65] op_sel_hi:[1,0]
	s_nop 0
	v_fma_f32 v3, -v6, v6, v7
	v_max_f32_e32 v3, 0, v3
	v_add_f32_e32 v3, 0x3727c5ac, v3
	v_cmp_gt_f32_e32 vcc, s35, v3
	v_mul_f32_e32 v4, 0x4b800000, v3
	s_nop 0
	v_cndmask_b32_e32 v3, v3, v4, vcc
	v_rsq_f32_e32 v3, v3
	s_nop 0
	v_mul_f32_e32 v4, 0x45800000, v3
	v_cndmask_b32_e32 v4, v3, v4, vcc
	v_add_u32_e32 v3, 0x4000, v44
	ds_read2_b64 v[14:17], v3 offset1:16
	v_add_u32_e32 v3, 0x6000, v44
	s_waitcnt lgkmcnt(0)
	v_pk_add_f32 v[20:21], v[12:13], v[14:15]
	ds_read2_b64 v[12:15], v3 offset1:16
	v_pk_add_f32 v[16:17], v[18:19], v[16:17]
	v_add_u32_e32 v3, 0x8000, v44
	s_waitcnt lgkmcnt(0)
	v_pk_add_f32 v[18:19], v[20:21], v[12:13]
	v_pk_add_f32 v[16:17], v[16:17], v[14:15]
	ds_read2_b64 v[12:15], v3 offset1:16
	v_add_u32_e32 v3, 0xa000, v44
	s_waitcnt lgkmcnt(0)
	v_pk_add_f32 v[18:19], v[18:19], v[12:13]
	v_pk_add_f32 v[16:17], v[16:17], v[14:15]
	ds_read2_b64 v[12:15], v3 offset1:16
	v_add_u32_e32 v3, 0xc000, v44
	s_waitcnt lgkmcnt(0)
	v_pk_add_f32 v[18:19], v[18:19], v[12:13]
	v_pk_add_f32 v[16:17], v[16:17], v[14:15]
	ds_read2_b64 v[12:15], v3 offset1:16
	v_add_u32_e32 v3, 0xe000, v44
	s_waitcnt lgkmcnt(0)
	v_pk_add_f32 v[18:19], v[18:19], v[12:13]
	v_pk_add_f32 v[16:17], v[16:17], v[14:15]
	ds_read2_b64 v[12:15], v3 offset1:16
	s_waitcnt lgkmcnt(0)
	v_pk_add_f32 v[18:19], v[18:19], v[12:13]
	v_pk_add_f32 v[16:17], v[16:17], v[14:15]
	v_mov_b64_e32 v[12:13], v[98:99]
	v_mov_b64_e32 v[14:15], v[100:101]
	s_waitcnt vmcnt(0) lgkmcnt(0)
	v_cvt_f64_i32_e32 v[20:21], v15
	v_ldexp_f64 v[20:21], v[20:21], 32
	v_cvt_f64_u32_e32 v[14:15], v14
	v_add_f64 v[14:15], v[20:21], v[14:15]
	v_cvt_f64_i32_e32 v[20:21], v13
	v_ldexp_f64 v[20:21], v[20:21], 32
	v_cvt_f64_u32_e32 v[12:13], v12
	v_add_f64 v[12:13], v[20:21], v[12:13]
	v_ldexp_f64 v[12:13], v[12:13], s2
	v_ldexp_f64 v[14:15], v[14:15], s2
	v_cvt_f32_f64_e32 v15, v[14:15]
	v_cvt_f32_f64_e32 v14, v[12:13]
	v_pk_fma_f32 v[18:19], v[6:7], v[14:15], v[18:19] op_sel_hi:[0,1,1] neg_lo:[1,0,0] neg_hi:[1,0,0]
	v_mov_b64_e32 v[12:13], v[102:103]
	v_mov_b64_e32 v[14:15], v[104:105]
	s_waitcnt vmcnt(0) lgkmcnt(0)
	v_cvt_f64_i32_e32 v[20:21], v15
	v_ldexp_f64 v[20:21], v[20:21], 32
	v_cvt_f64_u32_e32 v[14:15], v14
	v_add_f64 v[14:15], v[20:21], v[14:15]
	v_cvt_f64_i32_e32 v[20:21], v13
	v_ldexp_f64 v[20:21], v[20:21], 32
	v_cvt_f64_u32_e32 v[12:13], v12
	v_add_f64 v[12:13], v[20:21], v[12:13]
	v_ldexp_f64 v[12:13], v[12:13], s2
	v_ldexp_f64 v[14:15], v[14:15], s2
	v_cvt_f32_f64_e32 v15, v[14:15]
	v_cvt_f32_f64_e32 v14, v[12:13]
	v_mov_b64_e32 v[10:11], v[106:107]
	v_mov_b64_e32 v[12:13], v[108:109]
	v_pk_fma_f32 v[14:15], v[18:19], v[4:5], v[14:15] op_sel_hi:[1,0,1]
	s_waitcnt vmcnt(0) lgkmcnt(0)
	v_cvt_f64_i32_e32 v[18:19], v13
	v_ldexp_f64 v[18:19], v[18:19], 32
	v_cvt_f64_u32_e32 v[12:13], v12
	v_add_f64 v[12:13], v[18:19], v[12:13]
	v_cvt_f64_i32_e32 v[18:19], v11
	v_ldexp_f64 v[18:19], v[18:19], 32
	v_cvt_f64_u32_e32 v[10:11], v10
	v_add_f64 v[10:11], v[18:19], v[10:11]
	v_ldexp_f64 v[10:11], v[10:11], s2
	v_ldexp_f64 v[12:13], v[12:13], s2
	v_cvt_f32_f64_e32 v13, v[12:13]
	v_cvt_f32_f64_e32 v12, v[10:11]
	v_pk_fma_f32 v[10:11], v[6:7], v[12:13], v[16:17] op_sel_hi:[0,1,1] neg_lo:[1,0,0] neg_hi:[1,0,0]
	v_mov_b64_e32 v[6:7], v[110:111]
	v_mov_b64_e32 v[8:9], v[112:113]
	v_mul_f32_e32 v3, 0xbfb8aa3b, v14
	v_exp_f32_e32 v3, v3
	s_waitcnt vmcnt(0) lgkmcnt(0)
	v_cvt_f64_i32_e32 v[12:13], v9
	v_ldexp_f64 v[12:13], v[12:13], 32
	v_cvt_f64_u32_e32 v[8:9], v8
	v_add_f64 v[8:9], v[12:13], v[8:9]
	v_cvt_f64_i32_e32 v[12:13], v7
	v_ldexp_f64 v[12:13], v[12:13], 32
	v_cvt_f64_u32_e32 v[6:7], v6
	v_add_f64 v[6:7], v[12:13], v[6:7]
	v_ldexp_f64 v[6:7], v[6:7], s2
	v_ldexp_f64 v[8:9], v[8:9], s2
	v_add_f32_e32 v3, 1.0, v3
	v_cvt_f32_f64_e32 v9, v[8:9]
	v_cvt_f32_f64_e32 v8, v[6:7]
	v_rcp_f32_e32 v6, v3
	v_mul_f32_e32 v3, 0xbfb8aa3b, v15
	v_exp_f32_e32 v3, v3
	v_pk_fma_f32 v[4:5], v[10:11], v[4:5], v[8:9] op_sel_hi:[1,0,1]
	v_add_f32_e32 v3, 1.0, v3
	v_rcp_f32_e32 v7, v3
	v_ashrrev_i32_e32 v3, 31, v2
	v_lshl_add_u64 v[2:3], v[2:3], 1, v[40:41]
	v_pk_mul_f32 v[6:7], v[14:15], v[6:7]
	s_nop 0
	v_pk_mul_f32 v[4:5], v[4:5], v[6:7]
	s_nop 0
	v_cvt_pk_bf16_f32 v4, v4, v5
	global_store_dword v[2:3], v4, off sc1
	s_waitcnt vmcnt(0) lgkmcnt(0)
	s_barrier
	s_cmp_lg_u32 s86, 0
	s_cbranch_scc1 .Ltail_sig_skip
	v_mov_b32_e32 v18, 0x3d00
	s_mov_b64 exec, 1
	global_atomic_add v18, v223, s[90:91]
	s_mov_b64 exec, -1
